# GDN state update with K=16 bf16 MFMAs fed from accumulator-layout D registers (no exec masking); adaLN GEMV loop issues its 4 weight loads together
# speedup vs baseline: 1.0351x; 1.0049x over previous
; __device__ __forceinline__ void phase0(const Params& p, char* smem) {
;     ...
; #pragma unroll 4
;         for (int kk = 0; kk < 64; ++kk) {
;           const float w = aw[(size_t)(k0 + kk) * 6144 + n];
;           const float4* sp = reinterpret_cast<const float4*>(lds + kk * 36);
; #pragma unroll
;           for (int r4 = 0; r4 < 9; ++r4) {
;             const float4 s = sp[r4];
;             acc[r4 * 4 + 0] += s.x * w; acc[r4 * 4 + 1] += s.y * w; acc[r4 * 4 + 2] += s.z * w; acc[r4 * 4 + 3] += s.w * w;
;           }
;         }
.LBB0_192:
	v_lshl_add_u64 v[50:51], v[16:17], 0, s[0:1]
	global_load_dword v52, v[50:51], off
	v_add_co_u32_e32 v116, vcc, s95, v50
	s_nop 1
	v_addc_co_u32_e32 v117, vcc, 0, v51, vcc
	global_load_dword v115, v[116:117], off
	v_add_co_u32_e32 v120, vcc, s33, v50
	s_nop 1
	v_addc_co_u32_e32 v121, vcc, 0, v51, vcc
	global_load_dword v118, v[120:121], off
	v_add_co_u32_e32 v122, vcc, s20, v50
	s_nop 1
	v_addc_co_u32_e32 v123, vcc, 0, v51, vcc
	global_load_dword v119, v[122:123], off
	v_mov_b32_e32 v114, s24
	v_add_co_u32_e32 v100, vcc, s95, v50
	ds_read_b128 v[54:57], v114
	ds_read_b128 v[72:75], v114 offset:16
	ds_read_b128 v[76:79], v114 offset:32
	ds_read_b128 v[80:83], v114 offset:48
	ds_read_b128 v[84:87], v114 offset:64
	ds_read_b128 v[88:91], v114 offset:80
	ds_read_b128 v[92:95], v114 offset:96
	ds_read_b128 v[96:99], v114 offset:112
	ds_read2_b32 v[58:59], v114 offset0:32 offset1:68
	v_addc_co_u32_e32 v101, vcc, 0, v51, vcc
	s_add_u32 s0, s0, 0x18000
	s_addc_u32 s1, s1, 0
	s_addk_i32 s24, 0x240
	s_cmp_eq_u32 s0, 0x180000
	s_waitcnt vmcnt(3) lgkmcnt(4)
	v_pk_fma_f32 v[86:87], v[52:53], v[86:87], v[30:31] op_sel_hi:[0,1,1]
	v_add_co_u32_e32 v30, vcc, s33, v50
	v_pk_fma_f32 v[84:85], v[52:53], v[84:85], v[32:33] op_sel_hi:[0,1,1]
	s_nop 0
	v_addc_co_u32_e32 v31, vcc, 0, v51, vcc
	v_add_co_u32_e32 v32, vcc, s20, v50
	v_pk_fma_f32 v[102:103], v[52:53], v[54:55], v[48:49] op_sel_hi:[0,1,1]
	v_pk_fma_f32 v[104:105], v[52:53], v[56:57], v[46:47] op_sel_hi:[0,1,1]
	ds_read_b128 v[46:49], v114 offset:144
	v_pk_fma_f32 v[72:73], v[52:53], v[72:73], v[44:45] op_sel_hi:[0,1,1]
	v_pk_fma_f32 v[74:75], v[52:53], v[74:75], v[42:43] op_sel_hi:[0,1,1]
	ds_read_b128 v[42:45], v114 offset:160
	v_pk_fma_f32 v[76:77], v[52:53], v[76:77], v[40:41] op_sel_hi:[0,1,1]
	v_pk_fma_f32 v[78:79], v[52:53], v[78:79], v[38:39] op_sel_hi:[0,1,1]
	ds_read_b128 v[38:41], v114 offset:176
	v_pk_fma_f32 v[80:81], v[52:53], v[80:81], v[36:37] op_sel_hi:[0,1,1]
	v_pk_fma_f32 v[82:83], v[52:53], v[82:83], v[34:35] op_sel_hi:[0,1,1]
	ds_read_b128 v[34:37], v114 offset:192
	v_addc_co_u32_e32 v33, vcc, 0, v51, vcc
	s_waitcnt lgkmcnt(7)
	v_pk_fma_f32 v[88:89], v[52:53], v[88:89], v[28:29] op_sel_hi:[0,1,1]
	v_pk_fma_f32 v[90:91], v[52:53], v[90:91], v[26:27] op_sel_hi:[0,1,1]
	ds_read_b128 v[26:29], v114 offset:208
	s_waitcnt lgkmcnt(7)
	v_pk_fma_f32 v[92:93], v[52:53], v[92:93], v[24:25] op_sel_hi:[0,1,1]
	v_pk_fma_f32 v[94:95], v[52:53], v[94:95], v[22:23] op_sel_hi:[0,1,1]
	ds_read_b128 v[22:25], v114 offset:224
	s_waitcnt lgkmcnt(7)
	v_pk_fma_f32 v[96:97], v[52:53], v[96:97], v[20:21] op_sel_hi:[0,1,1]
	v_pk_fma_f32 v[98:99], v[52:53], v[98:99], v[18:19] op_sel_hi:[0,1,1]
	ds_read_b128 v[18:21], v114 offset:240
	ds_read_b128 v[54:57], v114 offset:256
	s_waitcnt lgkmcnt(8)
	v_fmac_f32_e32 v70, v52, v58
	s_waitcnt vmcnt(2) lgkmcnt(7)
	v_mov_b32_e32 v100, v115
	v_pk_fma_f32 v[102:103], v[100:101], v[46:47], v[102:103] op_sel_hi:[0,1,1]
	v_pk_fma_f32 v[104:105], v[100:101], v[48:49], v[104:105] op_sel_hi:[0,1,1]
	ds_read_b128 v[46:49], v114 offset:288
	s_waitcnt lgkmcnt(6)
	v_pk_fma_f32 v[110:111], v[100:101], v[38:39], v[76:77] op_sel_hi:[0,1,1]
	v_pk_fma_f32 v[112:113], v[100:101], v[40:41], v[78:79] op_sel_hi:[0,1,1]
	ds_read_b128 v[38:41], v114 offset:320
	s_waitcnt lgkmcnt(6)
	v_pk_fma_f32 v[80:81], v[100:101], v[34:35], v[80:81] op_sel_hi:[0,1,1]
	ds_read_b128 v[32:35], v114 offset:336
	s_waitcnt lgkmcnt(6)
	v_pk_fma_f32 v[84:85], v[100:101], v[26:27], v[84:85] op_sel_hi:[0,1,1]
	v_pk_fma_f32 v[86:87], v[100:101], v[28:29], v[86:87] op_sel_hi:[0,1,1]
	ds_read_b128 v[26:29], v114 offset:352
	s_waitcnt lgkmcnt(6)
	v_pk_fma_f32 v[88:89], v[100:101], v[22:23], v[88:89] op_sel_hi:[0,1,1]
	v_pk_fma_f32 v[90:91], v[100:101], v[24:25], v[90:91] op_sel_hi:[0,1,1]
	ds_read_b128 v[22:25], v114 offset:368
	s_waitcnt lgkmcnt(6)
	v_pk_fma_f32 v[92:93], v[100:101], v[18:19], v[92:93] op_sel_hi:[0,1,1]
	v_pk_fma_f32 v[94:95], v[100:101], v[20:21], v[94:95] op_sel_hi:[0,1,1]
	ds_read_b128 v[18:21], v114 offset:384
	s_waitcnt lgkmcnt(6)
	v_pk_fma_f32 v[96:97], v[100:101], v[54:55], v[96:97] op_sel_hi:[0,1,1]
	v_pk_fma_f32 v[98:99], v[100:101], v[56:57], v[98:99] op_sel_hi:[0,1,1]
	ds_read_b128 v[54:57], v114 offset:400
	v_pk_fma_f32 v[106:107], v[100:101], v[42:43], v[72:73] op_sel_hi:[0,1,1]
	v_pk_fma_f32 v[108:109], v[100:101], v[44:45], v[74:75] op_sel_hi:[0,1,1]
	ds_read_b128 v[42:45], v114 offset:304
	v_pk_fma_f32 v[82:83], v[100:101], v[36:37], v[82:83] op_sel_hi:[0,1,1]
	v_fmac_f32_e32 v70, v100, v59
	ds_read2_b32 v[58:59], v114 offset0:104 offset1:140
	s_waitcnt vmcnt(1) lgkmcnt(8)
	v_mov_b32_e32 v30, v118
	v_pk_fma_f32 v[100:101], v[30:31], v[48:49], v[104:105] op_sel_hi:[0,1,1]
	ds_read_b128 v[72:75], v114 offset:432
	ds_read_b128 v[76:79], v114 offset:448
	s_waitcnt lgkmcnt(9)
	v_pk_fma_f32 v[104:105], v[30:31], v[38:39], v[110:111] op_sel_hi:[0,1,1]
	ds_read_b128 v[36:39], v114 offset:464
	s_waitcnt lgkmcnt(9)
	v_pk_fma_f32 v[80:81], v[30:31], v[32:33], v[80:81] op_sel_hi:[0,1,1]
	v_pk_fma_f32 v[82:83], v[30:31], v[34:35], v[82:83] op_sel_hi:[0,1,1]
	ds_read_b128 v[32:35], v114 offset:480
	s_waitcnt lgkmcnt(9)
	v_pk_fma_f32 v[84:85], v[30:31], v[26:27], v[84:85] op_sel_hi:[0,1,1]
	v_pk_fma_f32 v[86:87], v[30:31], v[28:29], v[86:87] op_sel_hi:[0,1,1]
	ds_read_b128 v[26:29], v114 offset:496
	s_waitcnt lgkmcnt(9)
	v_pk_fma_f32 v[88:89], v[30:31], v[22:23], v[88:89] op_sel_hi:[0,1,1]
	v_pk_fma_f32 v[90:91], v[30:31], v[24:25], v[90:91] op_sel_hi:[0,1,1]
	ds_read_b128 v[22:25], v114 offset:512
	s_waitcnt lgkmcnt(9)
; __device__ __forceinline__ void phase0(const Params& p, char* smem) {
;     ...
;         for (int kk = 0; kk < 64; ++kk) {
;           const float w = aw[(size_t)(k0 + kk) * 6144 + n];
;           const float4* sp = reinterpret_cast<const float4*>(lds + kk * 36);
; #pragma unroll
;           for (int r4 = 0; r4 < 9; ++r4) {
;             const float4 s = sp[r4];
;             acc[r4 * 4 + 0] += s.x * w; acc[r4 * 4 + 1] += s.y * w; acc[r4 * 4 + 2] += s.z * w; acc[r4 * 4 + 3] += s.w * w;
;           }
;         }
;       }
	v_pk_fma_f32 v[92:93], v[30:31], v[18:19], v[92:93] op_sel_hi:[0,1,1]
	v_pk_fma_f32 v[94:95], v[30:31], v[20:21], v[94:95] op_sel_hi:[0,1,1]
	ds_read_b128 v[18:21], v114 offset:528
	s_waitcnt lgkmcnt(9)
	v_pk_fma_f32 v[96:97], v[30:31], v[54:55], v[96:97] op_sel_hi:[0,1,1]
	v_pk_fma_f32 v[98:99], v[30:31], v[56:57], v[98:99] op_sel_hi:[0,1,1]
	ds_read_b128 v[54:57], v114 offset:544
	v_pk_fma_f32 v[46:47], v[30:31], v[46:47], v[102:103] op_sel_hi:[0,1,1]
	s_waitcnt lgkmcnt(9)
	v_pk_fma_f32 v[42:43], v[30:31], v[42:43], v[106:107] op_sel_hi:[0,1,1]
	v_pk_fma_f32 v[102:103], v[30:31], v[44:45], v[108:109] op_sel_hi:[0,1,1]
	v_pk_fma_f32 v[106:107], v[30:31], v[40:41], v[112:113] op_sel_hi:[0,1,1]
	s_waitcnt lgkmcnt(8)
	v_fmac_f32_e32 v70, v30, v58
	s_waitcnt vmcnt(0) lgkmcnt(7)
	v_mov_b32_e32 v50, v119
	v_pk_fma_f32 v[48:49], v[50:51], v[72:73], v[46:47] op_sel_hi:[0,1,1]
	v_pk_fma_f32 v[46:47], v[50:51], v[74:75], v[100:101] op_sel_hi:[0,1,1]
	s_waitcnt lgkmcnt(6)
	v_pk_fma_f32 v[44:45], v[50:51], v[76:77], v[42:43] op_sel_hi:[0,1,1]
	v_pk_fma_f32 v[42:43], v[50:51], v[78:79], v[102:103] op_sel_hi:[0,1,1]
	s_waitcnt lgkmcnt(5)
	v_pk_fma_f32 v[40:41], v[50:51], v[36:37], v[104:105] op_sel_hi:[0,1,1]
	v_pk_fma_f32 v[38:39], v[50:51], v[38:39], v[106:107] op_sel_hi:[0,1,1]
	s_waitcnt lgkmcnt(4)
	v_pk_fma_f32 v[36:37], v[50:51], v[32:33], v[80:81] op_sel_hi:[0,1,1]
	v_pk_fma_f32 v[34:35], v[50:51], v[34:35], v[82:83] op_sel_hi:[0,1,1]
	s_waitcnt lgkmcnt(3)
	v_pk_fma_f32 v[32:33], v[50:51], v[26:27], v[84:85] op_sel_hi:[0,1,1]
	v_pk_fma_f32 v[30:31], v[50:51], v[28:29], v[86:87] op_sel_hi:[0,1,1]
	s_waitcnt lgkmcnt(2)
	v_pk_fma_f32 v[28:29], v[50:51], v[22:23], v[88:89] op_sel_hi:[0,1,1]
	v_pk_fma_f32 v[26:27], v[50:51], v[24:25], v[90:91] op_sel_hi:[0,1,1]
	s_waitcnt lgkmcnt(1)
	v_pk_fma_f32 v[24:25], v[50:51], v[18:19], v[92:93] op_sel_hi:[0,1,1]
	v_pk_fma_f32 v[22:23], v[50:51], v[20:21], v[94:95] op_sel_hi:[0,1,1]
	s_waitcnt lgkmcnt(0)
	v_pk_fma_f32 v[20:21], v[50:51], v[54:55], v[96:97] op_sel_hi:[0,1,1]
	v_pk_fma_f32 v[18:19], v[50:51], v[56:57], v[98:99] op_sel_hi:[0,1,1]
	v_fmac_f32_e32 v70, v50, v59
	s_cbranch_scc0 .LBB0_192
	s_add_i32 s37, s37, 64
	s_mov_b64 s[0:1], 0x180000
	v_add_u32_e32 v71, 64, v71
	s_cmp_ge_u32 s37, s38
	v_lshl_add_u64 v[16:17], v[16:17], 0, s[0:1]
	s_cbranch_scc0 .LBB0_180
; __device__ __forceinline__ void phase0(const Params& p, char* smem) {
;     ...
;       float* modp = reinterpret_cast<float*>(p.ws + OFF_PB) + ((size_t)kq * 4 + l) * 33 * 6144;
; #pragma unroll
;       for (int r = 0; r < 33; ++r) modp[(size_t)r * 6144 + n] = acc[r];
;       __syncthreads();
	s_lshl_b32 s0, s36, 2
	s_add_u32 s0, s0, s34
	s_addc_u32 s1, 0, s35
	s_mul_i32 s1, s1, 0xc6000
	s_mul_hi_u32 s24, s0, 0xc6000
	s_add_i32 s24, s24, s1
	s_mul_i32 s0, s0, 0xc6000
	s_add_u32 s0, s11, s0
	s_addc_u32 s1, s15, s24
	v_lshl_add_u64 v[14:15], v[14:15], 2, s[0:1]
	v_add_co_u32_e32 v16, vcc, s95, v14
	s_mov_b32 s0, 0x18000
	s_nop 0
	v_addc_co_u32_e32 v17, vcc, 0, v15, vcc
	global_store_dword v[16:17], v49, off
	v_add_co_u32_e32 v16, vcc, s33, v14
	global_store_dword v[14:15], v48, off
	s_nop 0
	v_addc_co_u32_e32 v17, vcc, 0, v15, vcc
	global_store_dword v[16:17], v46, off
	v_add_co_u32_e32 v16, vcc, s20, v14
	s_mov_b64 s[24:25], -1
	s_nop 0
	v_addc_co_u32_e32 v17, vcc, 0, v15, vcc
	global_store_dword v[16:17], v47, off
	v_add_co_u32_e32 v16, vcc, s0, v14
	s_mov_b32 s0, 0x1e000
	s_nop 0
	v_addc_co_u32_e32 v17, vcc, 0, v15, vcc
	global_store_dword v[16:17], v44, off
	v_add_co_u32_e32 v16, vcc, s0, v14
	s_mov_b32 s0, 0x24000
	s_nop 0
	v_addc_co_u32_e32 v17, vcc, 0, v15, vcc
	global_store_dword v[16:17], v45, off
	v_add_co_u32_e32 v16, vcc, s0, v14
	s_mov_b32 s0, 0x2a000
	s_nop 0
	v_addc_co_u32_e32 v17, vcc, 0, v15, vcc
	global_store_dword v[16:17], v42, off
	v_add_co_u32_e32 v16, vcc, s0, v14
	s_mov_b32 s0, 0x30000
	s_nop 0
	v_addc_co_u32_e32 v17, vcc, 0, v15, vcc
	global_store_dword v[16:17], v43, off
	v_add_co_u32_e32 v16, vcc, s0, v14
	s_mov_b32 s0, 0x36000
	s_nop 0
	v_addc_co_u32_e32 v17, vcc, 0, v15, vcc
	global_store_dword v[16:17], v40, off
	v_add_co_u32_e32 v16, vcc, s0, v14
	s_mov_b32 s0, 0x3c000
	s_nop 0
	v_addc_co_u32_e32 v17, vcc, 0, v15, vcc
	global_store_dword v[16:17], v41, off
	v_add_co_u32_e32 v16, vcc, s0, v14
	s_mov_b32 s0, 0x42000
	s_nop 0
	v_addc_co_u32_e32 v17, vcc, 0, v15, vcc
	global_store_dword v[16:17], v38, off
	v_add_co_u32_e32 v16, vcc, s0, v14
	s_mov_b32 s0, 0x48000
	s_nop 0
	v_addc_co_u32_e32 v17, vcc, 0, v15, vcc
	global_store_dword v[16:17], v39, off
	v_add_co_u32_e32 v16, vcc, s0, v14
	s_mov_b32 s0, 0x4e000
	s_nop 0
	v_addc_co_u32_e32 v17, vcc, 0, v15, vcc
	global_store_dword v[16:17], v36, off
	v_add_co_u32_e32 v16, vcc, s0, v14
	s_mov_b32 s0, 0x54000
	s_nop 0
	v_addc_co_u32_e32 v17, vcc, 0, v15, vcc
	global_store_dword v[16:17], v37, off
	v_add_co_u32_e32 v16, vcc, s0, v14
	s_mov_b32 s0, 0x5a000
	s_nop 0
	v_addc_co_u32_e32 v17, vcc, 0, v15, vcc
	global_store_dword v[16:17], v34, off
	v_add_co_u32_e32 v16, vcc, s0, v14
	s_mov_b32 s0, 0x60000
	s_nop 0
	v_addc_co_u32_e32 v17, vcc, 0, v15, vcc
	global_store_dword v[16:17], v35, off
	v_add_co_u32_e32 v16, vcc, s0, v14
	s_mov_b32 s0, 0x66000
	s_nop 0
	v_addc_co_u32_e32 v17, vcc, 0, v15, vcc
	global_store_dword v[16:17], v32, off
	v_add_co_u32_e32 v16, vcc, s0, v14
	s_mov_b32 s0, 0x6c000
	s_nop 0
	v_addc_co_u32_e32 v17, vcc, 0, v15, vcc
	global_store_dword v[16:17], v33, off
	v_add_co_u32_e32 v16, vcc, s0, v14
	s_mov_b32 s0, 0x72000
	s_nop 0
	v_addc_co_u32_e32 v17, vcc, 0, v15, vcc
	global_store_dword v[16:17], v30, off
	v_add_co_u32_e32 v16, vcc, s0, v14
	s_mov_b32 s0, 0x78000
	s_nop 0
	v_addc_co_u32_e32 v17, vcc, 0, v15, vcc
	global_store_dword v[16:17], v31, off
	v_add_co_u32_e32 v16, vcc, s0, v14
	s_mov_b32 s0, 0x7e000
	s_nop 0
	v_addc_co_u32_e32 v17, vcc, 0, v15, vcc
	global_store_dword v[16:17], v28, off
	v_add_co_u32_e32 v16, vcc, s0, v14
	s_mov_b32 s0, 0x84000
	s_nop 0
	v_addc_co_u32_e32 v17, vcc, 0, v15, vcc
	global_store_dword v[16:17], v29, off
	v_add_co_u32_e32 v16, vcc, s0, v14
	s_mov_b32 s0, 0x8a000
	s_nop 0
	v_addc_co_u32_e32 v17, vcc, 0, v15, vcc
	global_store_dword v[16:17], v26, off
	v_add_co_u32_e32 v16, vcc, s0, v14
	s_mov_b32 s0, 0x90000
	s_nop 0
	v_addc_co_u32_e32 v17, vcc, 0, v15, vcc
	global_store_dword v[16:17], v27, off
	v_add_co_u32_e32 v16, vcc, s0, v14
	s_mov_b32 s0, 0x96000
	s_nop 0
	v_addc_co_u32_e32 v17, vcc, 0, v15, vcc
	global_store_dword v[16:17], v24, off
	v_add_co_u32_e32 v16, vcc, s0, v14
	s_mov_b32 s0, 0x9c000
	s_nop 0
	v_addc_co_u32_e32 v17, vcc, 0, v15, vcc
	global_store_dword v[16:17], v25, off
	v_add_co_u32_e32 v16, vcc, s0, v14
	s_mov_b32 s0, 0xa2000
	s_nop 0
	v_addc_co_u32_e32 v17, vcc, 0, v15, vcc
	global_store_dword v[16:17], v22, off
	v_add_co_u32_e32 v16, vcc, s0, v14
	s_mov_b32 s0, 0xa8000
	s_nop 0
	v_addc_co_u32_e32 v17, vcc, 0, v15, vcc
	global_store_dword v[16:17], v23, off
	v_add_co_u32_e32 v16, vcc, s0, v14
	s_mov_b64 s[38:39], s[84:85]
	s_nop 0
	v_addc_co_u32_e32 v17, vcc, 0, v15, vcc
	global_store_dword v[16:17], v20, off
	v_add_co_u32_e32 v16, vcc, 0xae000, v14
	s_nop 1
	v_addc_co_u32_e32 v17, vcc, 0, v15, vcc
	global_store_dword v[16:17], v21, off
	v_add_co_u32_e32 v16, vcc, 0xb4000, v14
	s_nop 1
	v_addc_co_u32_e32 v17, vcc, 0, v15, vcc
	global_store_dword v[16:17], v18, off
	v_add_co_u32_e32 v16, vcc, 0xba000, v14
	s_nop 1
	v_addc_co_u32_e32 v17, vcc, 0, v15, vcc
	v_add_co_u32_e32 v14, vcc, 0xc0000, v14
	global_store_dword v[16:17], v19, off
	s_nop 0
	v_addc_co_u32_e32 v15, vcc, 0, v15, vcc
	global_store_dword v[14:15], v70, off
	s_barrier

; __device__ __forceinline__ void gdn_block4(const Params& p, int l, int b, int h, int dir, char* smem, bool ctx_out) {
;     ...
;         f32x4 ks0 = f32x4{0.f, 0.f, 0.f, 0.f}, qs0 = f32x4{0.f, 0.f, 0.f, 0.f};
; #pragma unroll
;         for (int ks = 0; ks < 2; ++ks) {
;           const float* kr = Lk + (tb + fr) * 68;
;           const float* qr = Lq + (tb + fr) * 68;
;           const float4 c0 = *reinterpret_cast<const float4*>(kr + (2 * ks) * 16 + fq * 4), c1 = *reinterpret_cast<const float4*>(kr + (2 * ks + 1) * 16 + fq * 4);
;           const float4 d0 = *reinterpret_cast<const float4*>(qr + (2 * ks) * 16 + fq * 4), d1 = *reinterpret_cast<const float4*>(qr + (2 * ks + 1) * 16 + fq * 4);
;           const uint4 uc = make_uint4(pack2(c0.x, c0.y), pack2(c0.z, c0.w), pack2(c1.x, c1.y), pack2(c1.z, c1.w));
;           const uint4 ud = make_uint4(pack2(d0.x, d0.y), pack2(d0.z, d0.w), pack2(d1.x, d1.y), pack2(d1.z, d1.w));
;           const uint4 us = make_uint4(pack2(Sacc[2 * ks][0], Sacc[2 * ks][1]), pack2(Sacc[2 * ks][2], Sacc[2 * ks][3]),
;                                       pack2(Sacc[2 * ks + 1][0], Sacc[2 * ks + 1][1]), pack2(Sacc[2 * ks + 1][2], Sacc[2 * ks + 1][3]));
;           const bf16x8 sf = __builtin_bit_cast(bf16x8, us);
;           ks0 = __builtin_amdgcn_mfma_f32_16x16x32_bf16(__builtin_bit_cast(bf16x8, uc), sf, ks0, 0, 0, 0);
;           qs0 = __builtin_amdgcn_mfma_f32_16x16x32_bf16(__builtin_bit_cast(bf16x8, ud), sf, qs0, 0, 0, 0);
;         }
; #pragma unroll
;         for (int i = 0; i < 4; ++i) { KSs[(fq * 4 + i) * 16 + fr] = ks0[i]; QSs[(fq * 4 + i) * 16 + fr] = qs0[i]; }
;         WAVE_SYNC();
;         float dreg[4] = {0.f, 0.f, 0.f, 0.f};
;         float na1[4], na2[4], nbt, nec, nv, nks, nqs;
; #pragma unroll
;         for (int j = 0; j < 4; ++j) { na1[j] = A1[sq + 4 * j]; na2[j] = A2[sq + 4 * j]; }
;         nbt = Bts[0]; nec = Ecs[0]; nv = Lv[tb * 68 + wid * 16 + vq]; nks = KSs[vq]; nqs = QSs[vq];
; #pragma unroll
;         for (int t = 0; t < 16; ++t) {
;           float a1[4], a2[4];
; #pragma unroll
;           for (int j = 0; j < 4; ++j) { a1[j] = na1[j]; a2[j] = na2[j]; }
;           const float bt = nbt, ec = nec, vv = nv, ksv = nks, qsv = nqs;
;           if (t < 15) {
; #pragma unroll
;             for (int j = 0; j < (t + 4) / 4; ++j) na1[j] = A1[(t + 1) * 16 + sq + 4 * j];
; #pragma unroll
.LBB0_1241:
	s_or_b64 exec, exec, s[90:91]
	s_xor_b64 s[70:71], s[70:71], -1
	s_mov_b32 s90, 1
	s_andn2_b64 vcc, exec, s[70:71]
	s_mov_b64 s[70:71], 0
	s_cbranch_vccz .LBB0_1252
.LBB0_1242:
	s_lshl_b32 vcc_lo, s90, 4
	v_or_b32_e32 v2, vcc_lo, v97
	v_mul_u32_u24_e32 v2, 0x44, v2
	v_lshl_add_u32 v2, v2, 2, v125
	ds_read_b128 v[56:59], v2
	ds_read_b128 v[60:63], v2 offset:64
	ds_read_b128 v[64:67], v2 offset:8704
	ds_read_b128 v[68:71], v2 offset:8768
	s_mul_i32 s91, s90, 0xa00
	s_waitcnt lgkmcnt(3)
	v_cvt_pk_bf16_f32 v56, v56, v57
	v_cvt_pk_bf16_f32 v57, v58, v59
	s_waitcnt lgkmcnt(2)
	v_cvt_pk_bf16_f32 v58, v60, v61
	v_cvt_pk_bf16_f32 v59, v62, v63
	s_waitcnt lgkmcnt(1)
	v_cvt_pk_bf16_f32 v60, v64, v65
	v_cvt_pk_bf16_f32 v61, v66, v67
	s_waitcnt lgkmcnt(0)
	v_cvt_pk_bf16_f32 v62, v68, v69
	v_cvt_pk_bf16_f32 v63, v70, v71
	v_cvt_pk_bf16_f32 v64, v52, v53
	v_cvt_pk_bf16_f32 v65, v54, v55
	v_cvt_pk_bf16_f32 v66, v48, v49
	v_cvt_pk_bf16_f32 v67, v50, v51
	ds_read_b128 v[68:71], v2 offset:128
	s_add_i32 vcc_hi, s33, s91
	v_mfma_f32_16x16x32_bf16 v[56:59], v[56:59], v[64:67], 0
	v_lshl_add_u32 v73, v106, 2, vcc_hi
	s_mul_i32 s91, s90, 0x1100
	s_waitcnt lgkmcnt(0)
	v_cvt_pk_bf16_f32 v68, v68, v69
	v_mfma_f32_16x16x32_bf16 v[60:63], v[60:63], v[64:67], 0
	ds_read_b128 v[64:67], v2 offset:192
	ds_read_b128 v[132:135], v2 offset:8832
	ds_read_b128 v[136:139], v2 offset:8896
	v_cvt_pk_bf16_f32 v69, v70, v71
	v_add_u32_e32 v2, 0x400, v119
	s_waitcnt lgkmcnt(2)
	v_cvt_pk_bf16_f32 v70, v64, v65
	v_cvt_pk_bf16_f32 v71, v66, v67
	s_waitcnt lgkmcnt(1)
	v_cvt_pk_bf16_f32 v64, v132, v133
	v_cvt_pk_bf16_f32 v65, v134, v135
	s_waitcnt lgkmcnt(0)
	v_cvt_pk_bf16_f32 v66, v136, v137
	v_cvt_pk_bf16_f32 v67, v138, v139
	v_cvt_pk_bf16_f32 v132, v44, v45
	v_cvt_pk_bf16_f32 v133, v46, v47
	v_cvt_pk_bf16_f32 v134, v40, v41
	v_cvt_pk_bf16_f32 v135, v42, v43
	v_add_u32_e32 v86, 0x400, v73
	s_add_i32 s96, s79, s91
	v_mfma_f32_16x16x32_bf16 v[56:59], v[68:71], v[132:135], v[56:59]
	v_mov_b32_e32 v72, vcc_hi
	v_lshl_add_u32 v87, v107, 2, s96
	v_lshl_add_u32 v128, s90, 12, v127
	v_mfma_f32_16x16x32_bf16 v[60:63], v[64:67], v[132:135], v[60:63]
	v_lshlrev_b32_e32 v2, 2, v98
	v_add_u32_e32 v2, vcc_hi, v2
	ds_read_b128 v[64:67], v2 offset:2176
	ds_read_b128 v[68:71], v2 offset:2048
	v_lshl_or_b32 v3, v88, 4, v97
	v_mul_u32_u24_e32 v129, 0x110, v98
	v_lshl_add_u32 v129, v3, 2, v129
	v_add_u32_e32 v129, s96, v129
	ds_read_b32 v132, v129 offset:17408
	ds_read_b32 v133, v129 offset:17680
	ds_read_b32 v134, v129 offset:17952
	ds_read_b32 v135, v129 offset:18224
	v_and_b32_e32 v131, 60, v102
	v_sub_u32_e32 v131, v128, v131
	v_lshl_add_u32 v131, v97, 2, v131
	v_lshl_add_u32 v131, v98, 8, v131
	s_waitcnt lgkmcnt(0)
	v_mul_f32_e32 v136, v64, v68
	v_mul_f32_e32 v137, v65, v69
	v_mul_f32_e32 v138, v66, v70
	v_mul_f32_e32 v139, v67, v71
	v_mul_f32_e32 v132, v64, v132
	v_mul_f32_e32 v133, v65, v133
	v_mul_f32_e32 v134, v66, v134
	v_mul_f32_e32 v135, v67, v135
	v_fma_f32 v132, -v136, v56, v132
	v_fma_f32 v133, -v137, v57, v133
	v_fma_f32 v134, -v138, v58, v134
	v_fma_f32 v135, -v139, v59, v135
	v_mul_f32_e32 v60, v68, v60
	v_mul_f32_e32 v61, v69, v61
	v_mul_f32_e32 v62, v70, v62
	v_mul_f32_e32 v63, v71, v63
	ds_write2_b32 v119, v132, v133 offset1:16
	ds_write2_b32 v119, v134, v135 offset0:32 offset1:48
	ds_read2_b32 v[132:133], v73 offset0:0 offset1:4
	ds_read2_b32 v[134:135], v73 offset0:8 offset1:12
	ds_read_b32 v136, v108 offset:0
	ds_read2_b32 v[138:139], v73 offset0:16 offset1:20
	ds_read2_b32 v[140:141], v73 offset0:24 offset1:28
	ds_read_b32 v137, v108 offset:64
	ds_read2_b32 v[68:69], v73 offset0:32 offset1:36
	ds_read2_b32 v[70:71], v73 offset0:40 offset1:44
	ds_read_b32 v142, v108 offset:128
	v_mov_b32_e32 v64, 0
	v_mov_b32_e32 v65, 0
	v_mov_b32_e32 v66, 0
	v_mov_b32_e32 v67, 0
	s_waitcnt lgkmcnt(6)
	v_mul_f32_e32 v2, v133, v65
	v_fmac_f32_e32 v2, v134, v66
	v_fmac_f32_e32 v2, v135, v67
	v_fmac_f32_e32 v2, v132, v64
	ds_read2_b32 v[132:133], v73 offset0:48 offset1:52
	ds_read2_b32 v[134:135], v73 offset0:56 offset1:60
	v_add_f32_dpp v2, v2, v2 quad_perm:[1,0,3,2] row_mask:0xf bank_mask:0xf bound_ctrl:1
	s_nop 1
	v_add_f32_dpp v2, v2, v2 quad_perm:[2,3,0,1] row_mask:0xf bank_mask:0xf bound_ctrl:1
	v_sub_f32_e32 v3, v136, v2
	ds_read_b32 v136, v108 offset:192
	v_cndmask_b32_e64 v64, v64, v3, s[62:63]
	ds_write_b32 v123, v3 offset:2048
	s_waitcnt lgkmcnt(7)
	v_mul_f32_e32 v2, v139, v65
	v_fmac_f32_e32 v2, v140, v66
	v_fmac_f32_e32 v2, v141, v67
	v_fmac_f32_e32 v2, v138, v64
	ds_read2_b32 v[138:139], v73 offset0:64 offset1:68
	ds_read2_b32 v[140:141], v73 offset0:72 offset1:76
	v_add_f32_dpp v2, v2, v2 quad_perm:[1,0,3,2] row_mask:0xf bank_mask:0xf bound_ctrl:1
	s_nop 1
	v_add_f32_dpp v2, v2, v2 quad_perm:[2,3,0,1] row_mask:0xf bank_mask:0xf bound_ctrl:1
	v_sub_f32_e32 v129, v137, v2
	ds_read_b32 v137, v108 offset:256
	v_cndmask_b32_e64 v64, v64, v129, s[64:65]
	ds_write_b32 v123, v129 offset:2052
	s_waitcnt lgkmcnt(8)
	v_mul_f32_e32 v2, v69, v65
	v_fmac_f32_e32 v2, v70, v66
	v_fmac_f32_e32 v2, v71, v67
	v_fmac_f32_e32 v2, v68, v64
	ds_read2_b32 v[68:69], v73 offset0:80 offset1:84
	ds_read2_b32 v[70:71], v73 offset0:88 offset1:92
	v_add_f32_dpp v2, v2, v2 quad_perm:[1,0,3,2] row_mask:0xf bank_mask:0xf bound_ctrl:1
	s_nop 1
	v_add_f32_dpp v2, v2, v2 quad_perm:[2,3,0,1] row_mask:0xf bank_mask:0xf bound_ctrl:1
	v_sub_f32_e32 v3, v142, v2
	ds_read_b32 v142, v108 offset:320
	v_cndmask_b32_e64 v64, v64, v3, s[66:67]
	ds_write_b32 v123, v3 offset:2056
	s_waitcnt lgkmcnt(9)
; __device__ __forceinline__ void gdn_block4(const Params& p, int l, int b, int h, int dir, char* smem, bool ctx_out) {
;     ...
; #pragma unroll
;         for (int t = 0; t < 16; ++t) {
;           float a1[4], a2[4];
; #pragma unroll
;           for (int j = 0; j < 4; ++j) { a1[j] = na1[j]; a2[j] = na2[j]; }
;           const float bt = nbt, ec = nec, vv = nv, ksv = nks, qsv = nqs;
;           if (t < 15) {
; #pragma unroll
;             for (int j = 0; j < (t + 4) / 4; ++j) na1[j] = A1[(t + 1) * 16 + sq + 4 * j];
; #pragma unroll
;             for (int j = 0; j <= ((t + 1) >> 2); ++j) na2[j] = A2[(t + 1) * 16 + sq + 4 * j];
;             nbt = Bts[t + 1]; nec = Ecs[t + 1]; nv = Lv[(tb + t + 1) * 68 + wid * 16 + vq]; nks = KSs[(t + 1) * 16 + vq]; nqs = QSs[(t + 1) * 16 + vq];
;           }
;           float part = 0.f;
; #pragma unroll
;           for (int j = 0; j < (t + 3) / 4; ++j) part += a1[j] * dreg[j];
;           part = reduce4(part);
;           const float dt = bt * vv - bt * ec * ksv - part;
;           dreg[t >> 2] = (sq == (t & 3)) ? dt : dreg[t >> 2];
;           float po = 0.f;
; #pragma unroll
;           for (int j = 0; j <= (t >> 2); ++j) po += a2[j] * dreg[j];
;           po = reduce4(po);
;           Lo[(tb + t) * 64 + wid * 16 + vq] = ec * qsv + po;
;           DlT[vq * 16 + t] = dt;
;         }
	v_mul_f32_e32 v2, v133, v65
	v_fmac_f32_e32 v2, v134, v66
	v_fmac_f32_e32 v2, v135, v67
	v_fmac_f32_e32 v2, v132, v64
	ds_read2_b32 v[132:133], v73 offset0:96 offset1:100
	ds_read2_b32 v[134:135], v73 offset0:104 offset1:108
	v_add_f32_dpp v2, v2, v2 quad_perm:[1,0,3,2] row_mask:0xf bank_mask:0xf bound_ctrl:1
	s_nop 1
	v_add_f32_dpp v2, v2, v2 quad_perm:[2,3,0,1] row_mask:0xf bank_mask:0xf bound_ctrl:1
	v_sub_f32_e32 v129, v136, v2
	ds_read_b32 v136, v108 offset:384
	v_cndmask_b32_e64 v64, v64, v129, s[68:69]
	ds_write_b32 v123, v129 offset:2060
	s_waitcnt lgkmcnt(9)
	v_mul_f32_e32 v2, v139, v65
	v_fmac_f32_e32 v2, v140, v66
	v_fmac_f32_e32 v2, v141, v67
	v_fmac_f32_e32 v2, v138, v64
	ds_read2_b32 v[138:139], v73 offset0:112 offset1:116
	ds_read2_b32 v[140:141], v73 offset0:120 offset1:124
	v_add_f32_dpp v2, v2, v2 quad_perm:[1,0,3,2] row_mask:0xf bank_mask:0xf bound_ctrl:1
	s_nop 1
	v_add_f32_dpp v2, v2, v2 quad_perm:[2,3,0,1] row_mask:0xf bank_mask:0xf bound_ctrl:1
	v_sub_f32_e32 v3, v137, v2
	ds_read_b32 v137, v108 offset:448
	v_cndmask_b32_e64 v65, v65, v3, s[62:63]
	ds_write_b32 v123, v3 offset:2064
	s_waitcnt lgkmcnt(9)
	v_mul_f32_e32 v2, v68, v64
	v_fmac_f32_e32 v2, v70, v66
	v_fmac_f32_e32 v2, v71, v67
	v_fmac_f32_e32 v2, v69, v65
	ds_read2_b32 v[68:69], v73 offset0:128 offset1:132
	ds_read2_b32 v[70:71], v73 offset0:136 offset1:140
	v_add_f32_dpp v2, v2, v2 quad_perm:[1,0,3,2] row_mask:0xf bank_mask:0xf bound_ctrl:1
	s_nop 1
	v_add_f32_dpp v2, v2, v2 quad_perm:[2,3,0,1] row_mask:0xf bank_mask:0xf bound_ctrl:1
	v_sub_f32_e32 v129, v142, v2
	ds_read_b32 v142, v108 offset:512
	v_cndmask_b32_e64 v65, v65, v129, s[64:65]
	ds_write_b32 v123, v129 offset:2068
	s_waitcnt lgkmcnt(9)
	v_mul_f32_e32 v2, v132, v64
	v_fmac_f32_e32 v2, v134, v66
	v_fmac_f32_e32 v2, v135, v67
	v_fmac_f32_e32 v2, v133, v65
	ds_read2_b32 v[132:133], v73 offset0:144 offset1:148
	ds_read2_b32 v[134:135], v73 offset0:152 offset1:156
	v_add_f32_dpp v2, v2, v2 quad_perm:[1,0,3,2] row_mask:0xf bank_mask:0xf bound_ctrl:1
	s_nop 1
	v_add_f32_dpp v2, v2, v2 quad_perm:[2,3,0,1] row_mask:0xf bank_mask:0xf bound_ctrl:1
	v_sub_f32_e32 v3, v136, v2
	ds_read_b32 v136, v108 offset:576
	v_cndmask_b32_e64 v65, v65, v3, s[66:67]
	ds_write_b32 v123, v3 offset:2072
	s_waitcnt lgkmcnt(9)
	v_mul_f32_e32 v2, v138, v64
	v_fmac_f32_e32 v2, v140, v66
	v_fmac_f32_e32 v2, v141, v67
	v_fmac_f32_e32 v2, v139, v65
	ds_read2_b32 v[138:139], v73 offset0:160 offset1:164
	ds_read2_b32 v[140:141], v73 offset0:168 offset1:172
	v_add_f32_dpp v2, v2, v2 quad_perm:[1,0,3,2] row_mask:0xf bank_mask:0xf bound_ctrl:1
	s_nop 1
	v_add_f32_dpp v2, v2, v2 quad_perm:[2,3,0,1] row_mask:0xf bank_mask:0xf bound_ctrl:1
	v_sub_f32_e32 v129, v137, v2
	ds_read_b32 v137, v108 offset:640
	v_cndmask_b32_e64 v65, v65, v129, s[68:69]
	ds_write_b32 v123, v129 offset:2076
	s_waitcnt lgkmcnt(9)
	v_mul_f32_e32 v2, v68, v64
	v_fmac_f32_e32 v2, v70, v66
	v_fmac_f32_e32 v2, v71, v67
	v_fmac_f32_e32 v2, v69, v65
	ds_read2_b32 v[68:69], v73 offset0:176 offset1:180
	ds_read2_b32 v[70:71], v73 offset0:184 offset1:188
	v_add_f32_dpp v2, v2, v2 quad_perm:[1,0,3,2] row_mask:0xf bank_mask:0xf bound_ctrl:1
	s_nop 1
	v_add_f32_dpp v2, v2, v2 quad_perm:[2,3,0,1] row_mask:0xf bank_mask:0xf bound_ctrl:1
	v_sub_f32_e32 v3, v142, v2
	ds_read_b32 v142, v108 offset:704
	v_cndmask_b32_e64 v66, v66, v3, s[62:63]
	ds_write_b32 v123, v3 offset:2080
	s_waitcnt lgkmcnt(9)
	v_mul_f32_e32 v2, v132, v64
	v_fmac_f32_e32 v2, v133, v65
	v_fmac_f32_e32 v2, v135, v67
	v_fmac_f32_e32 v2, v134, v66
	ds_read2_b32 v[132:133], v73 offset0:192 offset1:196
	ds_read2_b32 v[134:135], v73 offset0:200 offset1:204
	v_add_f32_dpp v2, v2, v2 quad_perm:[1,0,3,2] row_mask:0xf bank_mask:0xf bound_ctrl:1
	s_nop 1
	v_add_f32_dpp v2, v2, v2 quad_perm:[2,3,0,1] row_mask:0xf bank_mask:0xf bound_ctrl:1
	v_sub_f32_e32 v129, v136, v2
	ds_read_b32 v136, v108 offset:768
	v_cndmask_b32_e64 v66, v66, v129, s[64:65]
	ds_write_b32 v123, v129 offset:2084
	s_waitcnt lgkmcnt(9)
	v_mul_f32_e32 v2, v138, v64
	v_fmac_f32_e32 v2, v139, v65
	v_fmac_f32_e32 v2, v141, v67
	v_fmac_f32_e32 v2, v140, v66
	ds_read2_b32 v[138:139], v73 offset0:208 offset1:212
	ds_read2_b32 v[140:141], v73 offset0:216 offset1:220
	v_add_f32_dpp v2, v2, v2 quad_perm:[1,0,3,2] row_mask:0xf bank_mask:0xf bound_ctrl:1
	s_nop 1
	v_add_f32_dpp v2, v2, v2 quad_perm:[2,3,0,1] row_mask:0xf bank_mask:0xf bound_ctrl:1
	v_sub_f32_e32 v3, v137, v2
	ds_read_b32 v137, v108 offset:832
	v_cndmask_b32_e64 v66, v66, v3, s[66:67]
	ds_write_b32 v123, v3 offset:2088
	s_waitcnt lgkmcnt(9)
; __device__ __forceinline__ void gdn_block4(const Params& p, int l, int b, int h, int dir, char* smem, bool ctx_out) {
;     ...
; #pragma unroll
;         for (int t = 0; t < 16; ++t) {
;           float a1[4], a2[4];
; #pragma unroll
;           for (int j = 0; j < 4; ++j) { a1[j] = na1[j]; a2[j] = na2[j]; }
;           const float bt = nbt, ec = nec, vv = nv, ksv = nks, qsv = nqs;
;           if (t < 15) {
; #pragma unroll
;             for (int j = 0; j < (t + 4) / 4; ++j) na1[j] = A1[(t + 1) * 16 + sq + 4 * j];
; #pragma unroll
;             for (int j = 0; j <= ((t + 1) >> 2); ++j) na2[j] = A2[(t + 1) * 16 + sq + 4 * j];
;             nbt = Bts[t + 1]; nec = Ecs[t + 1]; nv = Lv[(tb + t + 1) * 68 + wid * 16 + vq]; nks = KSs[(t + 1) * 16 + vq]; nqs = QSs[(t + 1) * 16 + vq];
;           }
;           float part = 0.f;
; #pragma unroll
;           for (int j = 0; j < (t + 3) / 4; ++j) part += a1[j] * dreg[j];
;           part = reduce4(part);
;           const float dt = bt * vv - bt * ec * ksv - part;
;           dreg[t >> 2] = (sq == (t & 3)) ? dt : dreg[t >> 2];
;           float po = 0.f;
; #pragma unroll
;           for (int j = 0; j <= (t >> 2); ++j) po += a2[j] * dreg[j];
;           po = reduce4(po);
;           Lo[(tb + t) * 64 + wid * 16 + vq] = ec * qsv + po;
;           DlT[vq * 16 + t] = dt;
;         }
;         WAVE_SYNC();
;         {
;           const float Dd = Ecs[15];
;           bf16x8 df = {0, 0, 0, 0, 0, 0, 0, 0};
;           float4 e0 = make_float4(0.f, 0.f, 0.f, 0.f), e1 = e0;
;           if (fq < 2) {
;             const float4 x0 = *reinterpret_cast<const float4*>(DlT + fr * 16 + fq * 8), x1 = *reinterpret_cast<const float4*>(DlT + fr * 16 + fq * 8 + 4);
;             const uint4 ux = make_uint4(pack2(x0.x, x0.y), pack2(x0.z, x0.w), pack2(x1.x, x1.y), pack2(x1.z, x1.w));
;             df = __builtin_bit_cast(bf16x8, ux);
;             e0 = *reinterpret_cast<const float4*>(E15 + fq * 8); e1 = *reinterpret_cast<const float4*>(E15 + fq * 8 + 4);
;           }
; #pragma unroll
;           for (int mt = 0; mt < 4; ++mt) {
;             bf16x8 kt = {0, 0, 0, 0, 0, 0, 0, 0};
;             if (fq < 2) {
;               const float4 x0 = *reinterpret_cast<const float4*>(LkT + (mt * 16 + fr) * 36 + tb + fq * 8), x1 = *reinterpret_cast<const float4*>(LkT + (mt * 16 + fr) * 36 + tb + fq * 8 + 4);
	v_mul_f32_e32 v2, v68, v64
	v_fmac_f32_e32 v2, v69, v65
	v_fmac_f32_e32 v2, v71, v67
	v_fmac_f32_e32 v2, v70, v66
	ds_read2_b32 v[68:69], v73 offset0:224 offset1:228
	ds_read2_b32 v[70:71], v73 offset0:232 offset1:236
	v_add_f32_dpp v2, v2, v2 quad_perm:[1,0,3,2] row_mask:0xf bank_mask:0xf bound_ctrl:1
	s_nop 1
	v_add_f32_dpp v2, v2, v2 quad_perm:[2,3,0,1] row_mask:0xf bank_mask:0xf bound_ctrl:1
	v_sub_f32_e32 v129, v142, v2
	ds_read_b32 v142, v108 offset:896
	v_cndmask_b32_e64 v66, v66, v129, s[68:69]
	ds_write_b32 v123, v129 offset:2092
	s_waitcnt lgkmcnt(9)
	v_mul_f32_e32 v2, v132, v64
	v_fmac_f32_e32 v2, v133, v65
	v_fmac_f32_e32 v2, v135, v67
	v_fmac_f32_e32 v2, v134, v66
	ds_read2_b32 v[132:133], v73 offset0:240 offset1:244
	ds_read2_b32 v[134:135], v73 offset0:248 offset1:252
	v_add_f32_dpp v2, v2, v2 quad_perm:[1,0,3,2] row_mask:0xf bank_mask:0xf bound_ctrl:1
	s_nop 1
	v_add_f32_dpp v2, v2, v2 quad_perm:[2,3,0,1] row_mask:0xf bank_mask:0xf bound_ctrl:1
	v_sub_f32_e32 v3, v136, v2
	ds_read_b32 v136, v108 offset:960
	v_cndmask_b32_e64 v67, v67, v3, s[62:63]
	ds_write_b32 v123, v3 offset:2096
	s_waitcnt lgkmcnt(9)
	v_mul_f32_e32 v2, v138, v64
	v_fmac_f32_e32 v2, v139, v65
	v_fmac_f32_e32 v2, v140, v66
	v_fmac_f32_e32 v2, v141, v67
	s_nop 1
	v_add_f32_dpp v2, v2, v2 quad_perm:[1,0,3,2] row_mask:0xf bank_mask:0xf bound_ctrl:1
	s_nop 1
	v_add_f32_dpp v2, v2, v2 quad_perm:[2,3,0,1] row_mask:0xf bank_mask:0xf bound_ctrl:1
	v_sub_f32_e32 v129, v137, v2
	v_cndmask_b32_e64 v67, v67, v129, s[64:65]
	ds_write_b32 v123, v129 offset:2100
	s_waitcnt lgkmcnt(6)
	v_mul_f32_e32 v2, v68, v64
	v_fmac_f32_e32 v2, v69, v65
	v_fmac_f32_e32 v2, v70, v66
	v_fmac_f32_e32 v2, v71, v67
	s_nop 1
	v_add_f32_dpp v2, v2, v2 quad_perm:[1,0,3,2] row_mask:0xf bank_mask:0xf bound_ctrl:1
	s_nop 1
	v_add_f32_dpp v2, v2, v2 quad_perm:[2,3,0,1] row_mask:0xf bank_mask:0xf bound_ctrl:1
	v_sub_f32_e32 v3, v142, v2
	v_cndmask_b32_e64 v67, v67, v3, s[66:67]
	ds_write_b32 v123, v3 offset:2104
	s_waitcnt lgkmcnt(3)
	v_mul_f32_e32 v2, v132, v64
	v_fmac_f32_e32 v2, v133, v65
	v_fmac_f32_e32 v2, v134, v66
	v_fmac_f32_e32 v2, v135, v67
	s_nop 1
	v_add_f32_dpp v2, v2, v2 quad_perm:[1,0,3,2] row_mask:0xf bank_mask:0xf bound_ctrl:1
	s_nop 1
	v_add_f32_dpp v2, v2, v2 quad_perm:[2,3,0,1] row_mask:0xf bank_mask:0xf bound_ctrl:1
	v_sub_f32_e32 v129, v136, v2
	v_cndmask_b32_e64 v67, v67, v129, s[68:69]
	ds_write_b32 v123, v129 offset:2108
	v_lshlrev_b32_e32 v2, 2, v98
	v_sub_u32_e32 v3, v111, v2
	ds_read_b128 v[56:59], v3 offset:2048
	v_lshl_add_u32 v2, v97, 6, v2
	v_add_u32_e32 v2, vcc_hi, v2
	ds_read_b128 v[132:135], v2 offset:1024
	s_waitcnt lgkmcnt(0)
	v_mfma_f32_16x16x4_f32 v[60:63], v132, v56, v[60:63]
	v_mfma_f32_16x16x4_f32 v[60:63], v133, v57, v[60:63]
	v_mfma_f32_16x16x4_f32 v[60:63], v134, v58, v[60:63]
	v_mfma_f32_16x16x4_f32 v[60:63], v135, v59, v[60:63]
	s_nop 9
	ds_write_b32 v131, v60
	ds_write_b32 v131, v61 offset:256
	ds_write_b32 v131, v62 offset:512
	ds_write_b32 v131, v63 offset:768
	v_cvt_pk_bf16_f32 v64, v56, v57
	v_cvt_pk_bf16_f32 v65, v58, v59
	v_lshlrev_b32_e32 v2, 2, v98
	v_add_u32_e32 v3, vcc_hi, v2
	ds_read_b128 v[132:135], v3 offset:2112
	ds_read_b32 v128, v72 offset:2108
	v_lshl_add_u32 v3, vcc_lo, 2, v120
	v_add3_u32 v3, v3, v2, s79
	ds_read_b128 v[136:139], v3 offset:26112
	ds_read_b128 v[68:71], v3 offset:28416
	ds_read_b128 v[60:63], v3 offset:30720
	ds_read_b128 v[56:59], v3 offset:33024
	s_waitcnt lgkmcnt(3)
	v_pk_mul_f32 v[136:137], v[132:133], v[136:137]
	v_pk_mul_f32 v[138:139], v[134:135], v[138:139]
	v_pk_mul_f32 v[52:53], v[52:53], v[128:129] op_sel_hi:[1,0]
	v_pk_mul_f32 v[54:55], v[54:55], v[128:129] op_sel_hi:[1,0]
	v_cvt_pk_bf16_f32 v2, v136, v137
	v_cvt_pk_bf16_f32 v3, v138, v139
	s_nop 1
	v_mfma_f32_16x16x16_bf16 v[52:55], v[2:3], v[64:65], v[52:55]
	s_waitcnt lgkmcnt(2)
	v_pk_mul_f32 v[68:69], v[132:133], v[68:69]
	v_pk_mul_f32 v[70:71], v[134:135], v[70:71]
	v_pk_mul_f32 v[48:49], v[48:49], v[128:129] op_sel_hi:[1,0]
	v_pk_mul_f32 v[50:51], v[50:51], v[128:129] op_sel_hi:[1,0]
	v_cvt_pk_bf16_f32 v86, v68, v69
	v_cvt_pk_bf16_f32 v87, v70, v71
	s_nop 1
	v_mfma_f32_16x16x16_bf16 v[48:51], v[86:87], v[64:65], v[48:51]
	s_waitcnt lgkmcnt(1)
	v_pk_mul_f32 v[60:61], v[132:133], v[60:61]
	v_pk_mul_f32 v[62:63], v[134:135], v[62:63]
	v_pk_mul_f32 v[44:45], v[44:45], v[128:129] op_sel_hi:[1,0]
	v_pk_mul_f32 v[46:47], v[46:47], v[128:129] op_sel_hi:[1,0]
	v_cvt_pk_bf16_f32 v72, v60, v61
	v_cvt_pk_bf16_f32 v73, v62, v63
	s_nop 1
	v_mfma_f32_16x16x16_bf16 v[44:47], v[72:73], v[64:65], v[44:47]
	s_waitcnt lgkmcnt(0)
	v_pk_mul_f32 v[56:57], v[132:133], v[56:57]
	v_pk_mul_f32 v[58:59], v[134:135], v[58:59]
	v_pk_mul_f32 v[40:41], v[40:41], v[128:129] op_sel_hi:[1,0]
	v_pk_mul_f32 v[42:43], v[42:43], v[128:129] op_sel_hi:[1,0]
	v_cvt_pk_bf16_f32 v66, v56, v57
	v_cvt_pk_bf16_f32 v67, v58, v59
	s_nop 1
	v_mfma_f32_16x16x16_bf16 v[40:43], v[66:67], v[64:65], v[40:43]
	s_branch .LBB0_1241
